# FFN k-loop variant: all LDS stores in first MFMA group, global loads in second
# baseline (speedup 1.0000x reference)
.Lk5_loop:
	ds_read_b128 v[172:175], v168 offset:18464
	ds_read_b128 v[176:179], v168 offset:23072
	ds_read_b128 v[180:183], v169 offset:32
	ds_read_b128 v[184:187], v169 offset:4640
	s_waitcnt lgkmcnt(4)
	v_mfma_f32_32x32x16_bf16 v[50:65], v[102:105], v[106:109], v[50:65]
	s_waitcnt vmcnt(7)
	ds_write_b128 v140, v[66:69] offset:36864
	s_waitcnt vmcnt(6)
	ds_write_b128 v140, v[74:77] offset:55296
	v_mfma_f32_32x32x16_bf16 v[34:49], v[94:97], v[106:109], v[34:49]
	s_waitcnt vmcnt(5)
	ds_write_b128 v142, v[70:73] offset:36864
	s_waitcnt vmcnt(4)
	ds_write_b128 v142, v[82:85] offset:55296
	v_mfma_f32_32x32x16_bf16 v[18:33], v[102:105], v[98:101], v[18:33]
	s_waitcnt vmcnt(3)
	ds_write_b128 v144, v[78:81] offset:36864
	s_waitcnt vmcnt(2)
	ds_write_b128 v144, v[86:89] offset:55296
	v_mfma_f32_32x32x16_bf16 v[2:17], v[94:97], v[98:101], v[2:17]
	s_waitcnt vmcnt(1)
	ds_write_b128 v146, v[90:93] offset:36864
	s_waitcnt vmcnt(0)
	ds_write_b128 v146, v[110:113] offset:55296
	ds_read_b128 v[102:105], v168 offset:18496
	ds_read_b128 v[94:97], v168 offset:23104
	ds_read_b128 v[106:109], v169 offset:64
	ds_read_b128 v[98:101], v169 offset:4672
	s_waitcnt lgkmcnt(4)
	v_mfma_f32_32x32x16_bf16 v[50:65], v[172:175], v[180:183], v[50:65]
	s_mov_b64 exec, s[4:5]
	v_lshl_add_u64 v[66:67], v[134:135], 0, s[64:65]
	global_load_dwordx4 v[66:69], v[66:67], off
	s_mov_b64 exec, -1
	v_lshl_add_u64 v[74:75], v[220:221], 0, s[64:65]
	global_load_dwordx4 v[74:77], v[74:75], off
	v_mfma_f32_32x32x16_bf16 v[34:49], v[176:179], v[180:183], v[34:49]
	s_mov_b64 exec, s[6:7]
	v_lshl_add_u64 v[70:71], v[132:133], 0, s[64:65]
	global_load_dwordx4 v[70:73], v[70:71], off
	s_mov_b64 exec, -1
	v_lshl_add_u64 v[82:83], v[222:223], 0, s[64:65]
	global_load_dwordx4 v[82:85], v[82:83], off
	v_mfma_f32_32x32x16_bf16 v[18:33], v[172:175], v[184:187], v[18:33]
	s_mov_b64 exec, s[8:9]
	v_lshl_add_u64 v[78:79], v[130:131], 0, s[64:65]
	global_load_dwordx4 v[78:81], v[78:79], off
	s_mov_b64 exec, -1
	v_lshl_add_u64 v[86:87], v[224:225], 0, s[64:65]
	global_load_dwordx4 v[86:89], v[86:87], off
	v_mfma_f32_32x32x16_bf16 v[2:17], v[176:179], v[184:187], v[2:17]
	s_mov_b64 exec, s[10:11]
	v_lshl_add_u64 v[90:91], v[128:129], 0, s[64:65]
	global_load_dwordx4 v[90:93], v[90:91], off
	s_mov_b64 exec, -1
	v_lshl_add_u64 v[110:111], v[226:227], 0, s[64:65]
	global_load_dwordx4 v[110:113], v[110:111], off
	s_add_u32 s64, s64, 0x4000
	s_addc_u32 s65, s65, 0
	ds_read_b128 v[172:175], v168 offset:18528
	ds_read_b128 v[176:179], v168 offset:23136
	ds_read_b128 v[180:183], v169 offset:96
	ds_read_b128 v[184:187], v169 offset:4704
	s_waitcnt lgkmcnt(4)
	v_mfma_f32_32x32x16_bf16 v[50:65], v[102:105], v[106:109], v[50:65]
	v_mfma_f32_32x32x16_bf16 v[34:49], v[94:97], v[106:109], v[34:49]
	v_mfma_f32_32x32x16_bf16 v[18:33], v[102:105], v[98:101], v[18:33]
	v_mfma_f32_32x32x16_bf16 v[2:17], v[94:97], v[98:101], v[2:17]
	s_waitcnt lgkmcnt(0)
	s_barrier
	ds_read_b128 v[102:105], v168 offset:55296
	ds_read_b128 v[94:97], v168 offset:59904
	ds_read_b128 v[106:109], v169 offset:36864
	ds_read_b128 v[98:101], v169 offset:41472
	v_mfma_f32_32x32x16_bf16 v[50:65], v[172:175], v[180:183], v[50:65]
	v_mfma_f32_32x32x16_bf16 v[34:49], v[176:179], v[180:183], v[34:49]
	v_mfma_f32_32x32x16_bf16 v[18:33], v[172:175], v[184:187], v[18:33]
	v_mfma_f32_32x32x16_bf16 v[2:17], v[176:179], v[184:187], v[2:17]
	ds_read_b128 v[172:175], v168 offset:55328
	ds_read_b128 v[176:179], v168 offset:59936
	ds_read_b128 v[180:183], v169 offset:36896
	ds_read_b128 v[184:187], v169 offset:41504
	s_waitcnt lgkmcnt(4)
	v_mfma_f32_32x32x16_bf16 v[50:65], v[102:105], v[106:109], v[50:65]
	s_waitcnt vmcnt(7)
	ds_write_b128 v140, v[66:69]
	s_waitcnt vmcnt(6)
	ds_write_b128 v140, v[74:77] offset:18432
	v_mfma_f32_32x32x16_bf16 v[34:49], v[94:97], v[106:109], v[34:49]
	s_waitcnt vmcnt(5)
	ds_write_b128 v142, v[70:73]
	s_waitcnt vmcnt(4)
	ds_write_b128 v142, v[82:85] offset:18432
	v_mfma_f32_32x32x16_bf16 v[18:33], v[102:105], v[98:101], v[18:33]
	s_waitcnt vmcnt(3)
	ds_write_b128 v144, v[78:81]
	s_waitcnt vmcnt(2)
	ds_write_b128 v144, v[86:89] offset:18432
	v_mfma_f32_32x32x16_bf16 v[2:17], v[94:97], v[98:101], v[2:17]
	s_waitcnt vmcnt(1)
	ds_write_b128 v146, v[90:93]
	s_waitcnt vmcnt(0)
	ds_write_b128 v146, v[110:113] offset:18432
	ds_read_b128 v[102:105], v168 offset:55360
	ds_read_b128 v[94:97], v168 offset:59968
	ds_read_b128 v[106:109], v169 offset:36928
	ds_read_b128 v[98:101], v169 offset:41536
	s_waitcnt lgkmcnt(4)
	v_mfma_f32_32x32x16_bf16 v[50:65], v[172:175], v[180:183], v[50:65]
	s_mov_b64 exec, s[4:5]
	v_lshl_add_u64 v[66:67], v[134:135], 0, s[64:65]
	global_load_dwordx4 v[66:69], v[66:67], off
	s_mov_b64 exec, -1
	v_lshl_add_u64 v[74:75], v[220:221], 0, s[64:65]
	global_load_dwordx4 v[74:77], v[74:75], off
	v_mfma_f32_32x32x16_bf16 v[34:49], v[176:179], v[180:183], v[34:49]
	s_mov_b64 exec, s[6:7]
	v_lshl_add_u64 v[70:71], v[132:133], 0, s[64:65]
	global_load_dwordx4 v[70:73], v[70:71], off
	s_mov_b64 exec, -1
	v_lshl_add_u64 v[82:83], v[222:223], 0, s[64:65]
	global_load_dwordx4 v[82:85], v[82:83], off
	v_mfma_f32_32x32x16_bf16 v[18:33], v[172:175], v[184:187], v[18:33]
	s_mov_b64 exec, s[8:9]
	v_lshl_add_u64 v[78:79], v[130:131], 0, s[64:65]
	global_load_dwordx4 v[78:81], v[78:79], off
	s_mov_b64 exec, -1
	v_lshl_add_u64 v[86:87], v[224:225], 0, s[64:65]
	global_load_dwordx4 v[86:89], v[86:87], off
	v_mfma_f32_32x32x16_bf16 v[2:17], v[176:179], v[184:187], v[2:17]
	s_mov_b64 exec, s[10:11]
	v_lshl_add_u64 v[90:91], v[128:129], 0, s[64:65]
	global_load_dwordx4 v[90:93], v[90:91], off
	s_mov_b64 exec, -1
	v_lshl_add_u64 v[110:111], v[226:227], 0, s[64:65]
	global_load_dwordx4 v[110:113], v[110:111], off
	s_add_u32 s64, s64, 0x4000
	s_addc_u32 s65, s65, 0
	ds_read_b128 v[172:175], v168 offset:55392
	ds_read_b128 v[176:179], v168 offset:60000
	ds_read_b128 v[180:183], v169 offset:36960
	ds_read_b128 v[184:187], v169 offset:41568
	s_waitcnt lgkmcnt(4)
	v_mfma_f32_32x32x16_bf16 v[50:65], v[102:105], v[106:109], v[50:65]
	v_mfma_f32_32x32x16_bf16 v[34:49], v[94:97], v[106:109], v[34:49]
	v_mfma_f32_32x32x16_bf16 v[18:33], v[102:105], v[98:101], v[18:33]
	v_mfma_f32_32x32x16_bf16 v[2:17], v[94:97], v[98:101], v[2:17]
	s_waitcnt lgkmcnt(0)
	s_barrier
	ds_read_b128 v[102:105], v168 offset:18432
	ds_read_b128 v[94:97], v168 offset:23040
	ds_read_b128 v[106:109], v169
	ds_read_b128 v[98:101], v169 offset:4608
	v_mfma_f32_32x32x16_bf16 v[50:65], v[172:175], v[180:183], v[50:65]
	v_mfma_f32_32x32x16_bf16 v[34:49], v[176:179], v[180:183], v[34:49]
	v_mfma_f32_32x32x16_bf16 v[18:33], v[172:175], v[184:187], v[18:33]
	v_mfma_f32_32x32x16_bf16 v[2:17], v[176:179], v[184:187], v[2:17]
	s_sub_u32 s66, s66, 1
	s_cmp_lg_u32 s66, 0
	s_cbranch_scc1 .Lk5_loop
	s_branch .LBB0_679
